# seams: the globally last XCD leader no longer bumps the unused TOPGEN word (skips one atomic + its vmcnt(0) round trip on the last arriver's exit path)
# baseline (speedup 1.0000x reference)
.LBB0_397:
	s_or_b64 exec, exec, s[14:15]
	s_waitcnt vmcnt(0)
	v_readfirstlane_b32 s10, v4
	v_cvt_f32_u32_e32 v4, v2
	v_sub_u32_e32 v5, 0, v2
	v_add_u32_e32 v3, s10, v3
	v_readlane_b32 s10, v244, 1
	v_rcp_iflag_f32_e32 v4, v4
	v_readlane_b32 s11, v244, 2
	s_mov_b64 s[14:15], 0
	v_mul_f32_e32 v4, 0x4f7ffffe, v4
	v_cvt_u32_f32_e32 v4, v4
	v_mul_lo_u32 v5, v5, v4
	v_mul_hi_u32 v5, v4, v5
	v_add_u32_e32 v4, v4, v5
	v_mul_hi_u32 v4, v3, v4
	v_mul_lo_u32 v5, v4, v2
	v_sub_u32_e32 v5, v3, v5
	v_cmp_ge_u32_e32 vcc, v5, v2
	v_add_u32_e32 v6, 1, v4
	v_add_u32_e32 v3, 1, v3
	v_cndmask_b32_e32 v4, v4, v6, vcc
	v_sub_u32_e32 v6, v5, v2
	v_cndmask_b32_e32 v5, v5, v6, vcc
	v_cmp_ge_u32_e32 vcc, v5, v2
	v_add_u32_e32 v5, 1, v4
	s_nop 0
	v_cndmask_b32_e32 v4, v4, v5, vcc
	v_mul_lo_u32 v5, v2, v4
	v_add_u32_e32 v2, v5, v2
	v_mov_b32_e32 v204, v2
	v_cmp_ne_u32_e32 vcc, v3, v2
	v_mov_b64_e32 v[2:3], s[10:11]
	s_and_saveexec_b64 s[10:11], vcc
	s_cbranch_execz .LBB0_409
	v_readlane_b32 s14, v245, 63
	v_readlane_b32 s15, v244, 0
	s_mov_b64 s[18:19], 0
	s_nop 3
	global_load_dword v2, v173, s[14:15] sc1
	s_waitcnt vmcnt(0)
	v_cmp_lt_u32_e32 vcc, v2, v204
	s_and_saveexec_b64 s[14:15], vcc
	s_cbranch_execz .LBB0_408
	s_mov_b32 s39, 1
	s_branch .LBB0_401

.LBB0_1464:
	s_or_b64 exec, exec, s[14:15]
	s_waitcnt vmcnt(0)
	v_readfirstlane_b32 s10, v4
	v_cvt_f32_u32_e32 v4, v2
	v_sub_u32_e32 v5, 0, v2
	v_add_u32_e32 v3, s10, v3
	v_readlane_b32 s10, v244, 1
	v_rcp_iflag_f32_e32 v4, v4
	v_readlane_b32 s11, v244, 2
	s_mov_b64 s[14:15], 0
	v_mul_f32_e32 v4, 0x4f7ffffe, v4
	v_cvt_u32_f32_e32 v4, v4
	v_mul_lo_u32 v5, v5, v4
	v_mul_hi_u32 v5, v4, v5
	v_add_u32_e32 v4, v4, v5
	v_mul_hi_u32 v4, v3, v4
	v_mul_lo_u32 v5, v4, v2
	v_sub_u32_e32 v5, v3, v5
	v_cmp_ge_u32_e32 vcc, v5, v2
	v_add_u32_e32 v6, 1, v4
	v_add_u32_e32 v3, 1, v3
	v_cndmask_b32_e32 v4, v4, v6, vcc
	v_sub_u32_e32 v6, v5, v2
	v_cndmask_b32_e32 v5, v5, v6, vcc
	v_cmp_ge_u32_e32 vcc, v5, v2
	v_add_u32_e32 v5, 1, v4
	s_nop 0
	v_cndmask_b32_e32 v4, v4, v5, vcc
	v_mul_lo_u32 v5, v2, v4
	v_add_u32_e32 v2, v5, v2
	v_mov_b32_e32 v204, v2
	v_cmp_ne_u32_e32 vcc, v3, v2
	v_mov_b64_e32 v[2:3], s[10:11]
	s_and_saveexec_b64 s[10:11], vcc
	s_cbranch_execz .LBB0_1476
	v_readlane_b32 s14, v245, 63
	v_readlane_b32 s15, v244, 0
	s_mov_b64 s[18:19], 0
	s_nop 3
	global_load_dword v2, v173, s[14:15] sc1
	s_waitcnt vmcnt(0)
	v_cmp_lt_u32_e32 vcc, v2, v204
	s_and_saveexec_b64 s[14:15], vcc
	s_cbranch_execz .LBB0_1475
	s_mov_b32 s38, 1
	s_branch .LBB0_1468
